# m20: m19 + XCD-placement flag computed once per workgroup right after the first grid barrier (off the barrier leader's critical path)
# speedup vs baseline: 1.0166x; 1.0166x over previous
; __device__ __forceinline__ void xcd_barrier(const XcdBarrier& b) {
;     ...
;     __syncthreads();
; }
; __global__ void __launch_bounds__(512, 2) fwd_kernel(Args a0) {
;     ...
;         if (ph + 1 < ph_hi) {
;             if (ph_lo < 0) cg::this_grid().sync();
;             xcd_barrier(bar);
;         }
.LBB0_10:
	s_or_b64 exec, exec, s[40:41]
	s_waitcnt lgkmcnt(0)
	s_barrier
	s_mov_b64 s[40:41], 0
	s_cmp_lg_u32 s76, 1
	s_cbranch_scc1 .Lgb_flag_done
	s_load_dwordx2 s[44:45], s[60:61], 0xa0
	v_readlane_b32 s0, v254, 38
	s_waitcnt lgkmcnt(0)
	s_add_u32 s44, s44, 0xda04000
	s_addc_u32 s45, s45, 0
	v_mov_b32_e32 v18, s0
	v_mov_b32_e32 v20, 0
	global_load_dword v21, v20, s[44:45] sc1
	global_load_dword v22, v20, s[44:45] offset:256 sc1
	global_load_dword v23, v20, s[44:45] offset:512 sc1
	global_load_dword v24, v20, s[44:45] offset:768 sc1
	global_load_dword v25, v20, s[44:45] offset:1024 sc1
	global_load_dword v26, v20, s[44:45] offset:1280 sc1
	global_load_dword v27, v20, s[44:45] offset:1536 sc1
	global_load_dword v28, v20, s[44:45] offset:1792 sc1
	s_waitcnt vmcnt(0)
	v_add_u32_e32 v29, -1, v21
	v_and_b32_e32 v29, v29, v21
	v_mov_b32_e32 v30, v21
	v_add_u32_e32 v31, -1, v22
	v_and_b32_e32 v31, v31, v22
	v_or_b32_e32 v29, v29, v31
	v_min_u32_e32 v30, v30, v22
	v_add_u32_e32 v31, -1, v23
	v_and_b32_e32 v31, v31, v23
	v_or_b32_e32 v29, v29, v31
	v_min_u32_e32 v30, v30, v23
	v_add_u32_e32 v31, -1, v24
	v_and_b32_e32 v31, v31, v24
	v_or_b32_e32 v29, v29, v31
	v_min_u32_e32 v30, v30, v24
	v_add_u32_e32 v31, -1, v25
	v_and_b32_e32 v31, v31, v25
	v_or_b32_e32 v29, v29, v31
	v_min_u32_e32 v30, v30, v25
	v_add_u32_e32 v31, -1, v26
	v_and_b32_e32 v31, v31, v26
	v_or_b32_e32 v29, v29, v31
	v_min_u32_e32 v30, v30, v26
	v_add_u32_e32 v31, -1, v27
	v_and_b32_e32 v31, v31, v27
	v_or_b32_e32 v29, v29, v31
	v_min_u32_e32 v30, v30, v27
	v_add_u32_e32 v31, -1, v28
	v_and_b32_e32 v31, v31, v28
	v_or_b32_e32 v29, v29, v31
	v_min_u32_e32 v30, v30, v28
	v_cmp_eq_u32_e32 vcc, 0, v29
	v_cmp_ne_u32_e64 s[0:1], 0, v30
	s_nop 1
	s_and_b64 s[0:1], s[0:1], vcc
	s_and_b64 s[0:1], s[0:1], exec
	s_cselect_b32 s0, 1, 2
	v_mov_b32_e32 v19, s0
	ds_write_b32 v18, v19 offset:8
	s_waitcnt lgkmcnt(0)
.Lgb_flag_done:
.LBB0_11:
	s_and_b64 vcc, exec, s[40:41]
	s_cbranch_vccnz .LBB0_407
